# EpiSwiglu epilogue: packed f32 VALU ops split into scalar halves (136 per tile)
# baseline (speedup 1.0000x reference)
; __device__ __forceinline__ unsigned cvt_pk_bf16(float lo, float hi) { const f32x2 v = {lo, hi}; return __builtin_bit_cast(unsigned, __builtin_convertvector(v, bf16x2_t)); }
; __device__ __forceinline__ float fast_silu(float g) { return g * __builtin_amdgcn_rcpf(1.0f + __builtin_amdgcn_exp2f(-1.4426950408889634f * g)); }
; __device__ __forceinline__ float sum4(f32x4 v) { return (v.x + v.y) + (v.z + v.w); }
; __device__ __forceinline__ float quad_sum(float t, int lane) { t += shx(t, 16, lane); t += shx(t, 32, lane); return t; }
;     template <int A0, int A1> __device__ __forceinline__ void run(const f32x4 (&acc)[2][2][4][2], const Unit& u, int wr, int wc, int fr, int fq) const {
;         const int s = stream_of(u.pm);
;         const int cb = u.pn * 256 + wc * 32 + fq * 8;
;         const float* bp = sW + s * NFF + cb;
;         f32x4 bg[2], bu[2];
; #pragma unroll
;         for (int n = 0; n < 2; ++n) { bg[n] = *(const f32x4*)(bp + 4 * n); bu[n] = *(const f32x4*)(bp + 128 + 4 * n); }
;         const int row0 = u.pm * 256 + wr * 64 + fr;
; #pragma unroll
;         for (int ai = A0; ai < A1; ++ai)
; #pragma unroll
;             for (int m = 0; m < 4; ++m) {
;                 const int row = row0 + ai * 128 + m * 16;
;                 const float t = quad_sum(sum4(*(const f32x4*)(ssqp + (size_t)row * 16 + 4 * fq)), fq * 16 + fr);
;                 const float rr = rsqrtf(t * (1.0f / 1024.0f) + EPS);
;                 u32x4 w;
; #pragma unroll
;                 for (int n = 0; n < 2; ++n) {
;                     const f32x4 gg = acc[ai][0][m][n] * rr + bg[n], uu = acc[ai][1][m][n] * rr + bu[n];
;                     const float h0 = fast_silu(gg.x) * uu.x, h1 = fast_silu(gg.y) * uu.y, h2 = fast_silu(gg.z) * uu.z, h3 = fast_silu(gg.w) * uu.w;
;                     w[2 * n] = cvt_pk_bf16(h0, h1); w[2 * n + 1] = cvt_pk_bf16(h2, h3);
;                 }
;                 bf16_t* hp = H + (size_t)row * DFF + u.pn * 128 + wc * 32 + fq * 8;
;                 if (cnt) asm volatile("global_store_dwordx4 %0, %1, off sc0 sc1" :: "v"(hp), "v"(w) : "memory");
;                 else *(u32x4*)hp = w;
;             }
.LBB0_235:
	s_cmp_lt_u32 s16, 64
	s_cselect_b32 s7, s1, 0x2c00
	s_cmp_gt_i32 s16, 31
	s_cselect_b32 s7, s7, 0
	s_lshl_b32 s7, s7, 2
	v_lshl_add_u32 v160, s16, 8, v162
	v_lshl_or_b32 v32, s6, 8, v166
	s_add_u32 s20, s67, s7
	v_ashrrev_i32_e32 v161, 31, v160
	s_addc_u32 s21, s87, 0
	v_ashrrev_i32_e32 v33, 31, v32
	v_lshlrev_b64 v[168:169], 6, v[160:161]
	v_lshl_add_u64 v[40:41], v[32:33], 2, s[20:21]
	v_lshl_add_u64 v[168:169], v[154:155], 0, v[168:169]
	global_load_dwordx4 v[36:39], v[40:41], off offset:16
	global_load_dwordx4 v[44:47], v[40:41], off
	global_load_dwordx4 v[32:35], v[40:41], off offset:528
	s_nop 0
	global_load_dwordx4 v[40:43], v[40:41], off offset:512
	s_lshl_b32 s84, s6, 7
	global_load_dwordx4 v[224:227], v[168:169], off offset:1024
	global_load_dwordx4 v[228:231], v[168:169], off offset:2048
	global_load_dwordx4 v[232:235], v[168:169], off offset:3072
	v_mov_b32_e32 v236, 0x2000
	v_mov_b32_e32 v237, 0
	v_lshl_add_u64 v[236:237], v[168:169], 0, v[236:237]
	global_load_dwordx4 v[240:243], v[236:237], off
	global_load_dwordx4 v[244:247], v[236:237], off offset:1024
	global_load_dwordx4 v[248:251], v[236:237], off offset:2048
	global_load_dwordx4 v[168:171], v[168:169], off
	s_ashr_i32 s85, s84, 31
	s_waitcnt vmcnt(0)
	v_mov_b32_e32 v172, v169
	v_mov_b32_e32 v173, v170
	v_mov_b32_e32 v169, v171
	v_add_f32_e32 v168, v172, v168
	v_add_f32_e32 v169, v173, v169
	s_nop 0
	v_add_f32_e32 v161, v168, v169
	ds_bpermute_b32 v168, v164, v161
	s_waitcnt lgkmcnt(0)
	v_add_f32_e32 v161, v161, v168
	ds_bpermute_b32 v168, v165, v161
	s_waitcnt lgkmcnt(0)
	v_add_f32_e32 v161, v161, v168
	v_fmamk_f32 v161, v161, 0x3a800000, v252
	v_cmp_gt_f32_e32 vcc, s49, v161
	v_mul_f32_e32 v168, 0x4b800000, v161
	s_nop 0
	v_cndmask_b32_e32 v161, v161, v168, vcc
	v_rsq_f32_e32 v161, v161
	s_nop 0
	v_mul_f32_e32 v168, 0x45800000, v161
	v_cndmask_b32_e32 v168, v161, v168, vcc
	v_fma_f32 v142, v142, v168, v44
	v_fma_f32 v143, v143, v168, v45
	v_fma_f32 v144, v144, v168, v46
	v_fma_f32 v145, v145, v168, v47
	v_mul_f32_e32 v161, 0xbfb8aa3b, v142
	v_exp_f32_e32 v161, v161
	v_fma_f32 v134, v134, v168, v40
	v_fma_f32 v135, v135, v168, v41
	v_fma_f32 v136, v136, v168, v42
	v_fma_f32 v137, v137, v168, v43
	v_fma_f32 v138, v138, v168, v36
	v_fma_f32 v139, v139, v168, v37
	v_add_f32_e32 v161, 1.0, v161
	v_rcp_f32_e32 v170, v161
	v_mul_f32_e32 v161, 0xbfb8aa3b, v143
	v_exp_f32_e32 v161, v161
	v_fma_f32 v130, v130, v168, v32
	v_fma_f32 v131, v131, v168, v33
	v_fma_f32 v132, v132, v168, v34
	v_fma_f32 v133, v133, v168, v35
	s_andn2_b64 vcc, exec, s[24:25]
	v_add_f32_e32 v161, 1.0, v161
	v_rcp_f32_e32 v171, v161
	s_nop 0
	v_mul_f32_e32 v142, v142, v170
	v_mul_f32_e32 v143, v143, v171
	s_nop 0
	v_mul_f32_e32 v134, v134, v142
	v_mul_f32_e32 v135, v135, v143
	v_mul_f32_e32 v142, 0xbfb8aa3b, v144
	v_mul_f32_e32 v143, 0xbfb8aa3b, v145
	v_exp_f32_e32 v142, v142
	v_exp_f32_e32 v143, v143
	v_cvt_pk_bf16_f32 v134, v134, v135
	v_add_f32_e32 v142, 1.0, v142
	v_add_f32_e32 v143, 1.0, v143
	v_rcp_f32_e32 v142, v142
	v_rcp_f32_e32 v143, v143
	s_nop 0
	v_mul_f32_e32 v142, v144, v142
	v_mul_f32_e32 v143, v145, v143
	s_nop 0
	v_mul_f32_e32 v136, v136, v142
	v_mul_f32_e32 v137, v137, v143
	s_nop 0
	v_cvt_pk_bf16_f32 v135, v136, v137
	v_fma_f32 v136, v140, v168, v38
	v_fma_f32 v137, v141, v168, v39
	v_mul_f32_e32 v140, 0xbfb8aa3b, v138
	v_mul_f32_e32 v141, 0xbfb8aa3b, v139
	v_exp_f32_e32 v140, v140
	v_exp_f32_e32 v141, v141
	v_add_f32_e32 v140, 1.0, v140
	v_add_f32_e32 v141, 1.0, v141
	v_rcp_f32_e32 v140, v140
	v_rcp_f32_e32 v141, v141
	s_nop 0
	v_mul_f32_e32 v138, v138, v140
	v_mul_f32_e32 v139, v139, v141
	s_nop 0
	v_mul_f32_e32 v130, v130, v138
	v_mul_f32_e32 v131, v131, v139
	v_mul_f32_e32 v138, 0xbfb8aa3b, v136
	v_mul_f32_e32 v139, 0xbfb8aa3b, v137
	v_exp_f32_e32 v138, v138
	v_exp_f32_e32 v139, v139
	v_add_f32_e32 v138, 1.0, v138
	v_add_f32_e32 v139, 1.0, v139
	v_rcp_f32_e32 v138, v138
	v_rcp_f32_e32 v139, v139
	s_nop 0
	v_mul_f32_e32 v136, v136, v138
	v_mul_f32_e32 v137, v137, v139
	s_nop 0
	v_mul_f32_e32 v132, v132, v136
	v_mul_f32_e32 v133, v133, v137
	v_cvt_pk_bf16_f32 v136, v130, v131
	v_mov_b64_e32 v[130:131], s[12:13]
	v_mad_i64_i32 v[130:131], s[20:21], v160, s1, v[130:131]
	v_lshl_add_u64 v[130:131], s[84:85], 1, v[130:131]
	v_cvt_pk_bf16_f32 v137, v132, v133
	v_lshl_add_u64 v[130:131], v[130:131], 0, s[52:53]
	v_cndmask_b32_e64 v132, 0, 1, s[24:25]
	v_lshl_add_u64 v[130:131], v[130:131], 0, v[128:129]
	v_cmp_ne_u32_e64 s[6:7], 1, v132
	s_cbranch_vccnz .LBB0_267
	global_store_dwordx4 v[130:131], v[134:137], off sc0 sc1
	s_cbranch_execnz .LBB0_238

; __device__ __forceinline__ unsigned cvt_pk_bf16(float lo, float hi) { const f32x2 v = {lo, hi}; return __builtin_bit_cast(unsigned, __builtin_convertvector(v, bf16x2_t)); }
; __device__ __forceinline__ float fast_silu(float g) { return g * __builtin_amdgcn_rcpf(1.0f + __builtin_amdgcn_exp2f(-1.4426950408889634f * g)); }
; __device__ __forceinline__ float sum4(f32x4 v) { return (v.x + v.y) + (v.z + v.w); }
; __device__ __forceinline__ float quad_sum(float t, int lane) { t += shx(t, 16, lane); t += shx(t, 32, lane); return t; }
;     template <int A0, int A1> __device__ __forceinline__ void run(const f32x4 (&acc)[2][2][4][2], const Unit& u, int wr, int wc, int fr, int fq) const {
;     ...
;             for (int m = 0; m < 4; ++m) {
;                 const int row = row0 + ai * 128 + m * 16;
;                 const float t = quad_sum(sum4(*(const f32x4*)(ssqp + (size_t)row * 16 + 4 * fq)), fq * 16 + fr);
;                 const float rr = rsqrtf(t * (1.0f / 1024.0f) + EPS);
;                 u32x4 w;
; #pragma unroll
;                 for (int n = 0; n < 2; ++n) {
;                     const f32x4 gg = acc[ai][0][m][n] * rr + bg[n], uu = acc[ai][1][m][n] * rr + bu[n];
;                     const float h0 = fast_silu(gg.x) * uu.x, h1 = fast_silu(gg.y) * uu.y, h2 = fast_silu(gg.z) * uu.z, h3 = fast_silu(gg.w) * uu.w;
;                     w[2 * n] = cvt_pk_bf16(h0, h1); w[2 * n + 1] = cvt_pk_bf16(h2, h3);
;                 }
;                 bf16_t* hp = H + (size_t)row * DFF + u.pn * 128 + wc * 32 + fq * 8;
;                 if (cnt) asm volatile("global_store_dwordx4 %0, %1, off sc0 sc1" :: "v"(hp), "v"(w) : "memory");
;                 else *(u32x4*)hp = w;
.LBB0_238:
	v_or_b32_e32 v130, 16, v160
	v_ashrrev_i32_e32 v131, 31, v130
	v_mov_b64_e32 v[132:133], v[224:225]
	v_mov_b64_e32 v[134:135], v[226:227]
	global_load_dwordx4 v[224:227], v[236:237], off offset:3072
	v_mov_b32_e32 v136, v133
	v_mov_b32_e32 v137, v134
	v_mov_b32_e32 v133, v135
	v_add_f32_e32 v132, v136, v132
	v_add_f32_e32 v133, v137, v133
	s_nop 0
	v_add_f32_e32 v131, v132, v133
	ds_bpermute_b32 v132, v164, v131
	s_waitcnt lgkmcnt(0)
	v_add_f32_e32 v131, v131, v132
	ds_bpermute_b32 v132, v165, v131
	s_waitcnt lgkmcnt(0)
	v_add_f32_e32 v131, v131, v132
	v_fmamk_f32 v131, v131, 0x3a800000, v252
	v_cmp_gt_f32_e32 vcc, s49, v131
	v_mul_f32_e32 v132, 0x4b800000, v131
	s_nop 0
	v_cndmask_b32_e32 v131, v131, v132, vcc
	v_rsq_f32_e32 v131, v131
	s_nop 0
	v_mul_f32_e32 v132, 0x45800000, v131
	v_cndmask_b32_e32 v132, v131, v132, vcc
	v_fma_f32 v124, v124, v132, v44
	v_fma_f32 v125, v125, v132, v45
	v_fma_f32 v126, v126, v132, v46
	v_fma_f32 v127, v127, v132, v47
	v_mul_f32_e32 v131, 0xbfb8aa3b, v124
	v_exp_f32_e32 v131, v131
	v_fma_f32 v116, v116, v132, v40
	v_fma_f32 v117, v117, v132, v41
	v_fma_f32 v118, v118, v132, v42
	v_fma_f32 v119, v119, v132, v43
	v_fma_f32 v120, v120, v132, v36
	v_fma_f32 v121, v121, v132, v37
	v_add_f32_e32 v131, 1.0, v131
	v_rcp_f32_e32 v134, v131
	v_mul_f32_e32 v131, 0xbfb8aa3b, v125
	v_exp_f32_e32 v131, v131
	v_fma_f32 v112, v112, v132, v32
	v_fma_f32 v113, v113, v132, v33
	v_fma_f32 v114, v114, v132, v34
	v_fma_f32 v115, v115, v132, v35
	s_and_b64 vcc, exec, s[6:7]
	v_add_f32_e32 v131, 1.0, v131
	v_rcp_f32_e32 v135, v131
	s_nop 0
	v_mul_f32_e32 v124, v124, v134
	v_mul_f32_e32 v125, v125, v135
	s_nop 0
	v_mul_f32_e32 v116, v116, v124
	v_mul_f32_e32 v117, v117, v125
	v_mul_f32_e32 v124, 0xbfb8aa3b, v126
	v_mul_f32_e32 v125, 0xbfb8aa3b, v127
	v_exp_f32_e32 v124, v124
	v_exp_f32_e32 v125, v125
	v_cvt_pk_bf16_f32 v116, v116, v117
	v_add_f32_e32 v124, 1.0, v124
	v_add_f32_e32 v125, 1.0, v125
	v_rcp_f32_e32 v124, v124
	v_rcp_f32_e32 v125, v125
	s_nop 0
	v_mul_f32_e32 v124, v126, v124
	v_mul_f32_e32 v125, v127, v125
	s_nop 0
	v_mul_f32_e32 v118, v118, v124
	v_mul_f32_e32 v119, v119, v125
	s_nop 0
	v_cvt_pk_bf16_f32 v117, v118, v119
	v_fma_f32 v118, v122, v132, v38
	v_fma_f32 v119, v123, v132, v39
	v_mul_f32_e32 v122, 0xbfb8aa3b, v120
	v_mul_f32_e32 v123, 0xbfb8aa3b, v121
	v_exp_f32_e32 v122, v122
	v_exp_f32_e32 v123, v123
	v_add_f32_e32 v122, 1.0, v122
	v_add_f32_e32 v123, 1.0, v123
	v_rcp_f32_e32 v122, v122
	v_rcp_f32_e32 v123, v123
	s_nop 0
	v_mul_f32_e32 v120, v120, v122
	v_mul_f32_e32 v121, v121, v123
	s_nop 0
	v_mul_f32_e32 v112, v112, v120
	v_mul_f32_e32 v113, v113, v121
	v_mul_f32_e32 v120, 0xbfb8aa3b, v118
	v_mul_f32_e32 v121, 0xbfb8aa3b, v119
	v_exp_f32_e32 v120, v120
	v_exp_f32_e32 v121, v121
	v_add_f32_e32 v120, 1.0, v120
	v_add_f32_e32 v121, 1.0, v121
	v_rcp_f32_e32 v120, v120
	v_rcp_f32_e32 v121, v121
	s_nop 0
	v_mul_f32_e32 v118, v118, v120
	v_mul_f32_e32 v119, v119, v121
	s_nop 0
	v_mul_f32_e32 v114, v114, v118
	v_mul_f32_e32 v115, v115, v119
	v_cvt_pk_bf16_f32 v118, v112, v113
	v_mov_b64_e32 v[112:113], s[12:13]
	v_mad_i64_i32 v[112:113], s[20:21], v130, s1, v[112:113]
	v_lshl_add_u64 v[112:113], s[84:85], 1, v[112:113]
	v_lshl_add_u64 v[112:113], v[112:113], 0, s[52:53]
	v_cvt_pk_bf16_f32 v119, v114, v115
	v_lshl_add_u64 v[112:113], v[112:113], 0, v[128:129]
	s_cbranch_vccnz .LBB0_268
	global_store_dwordx4 v[112:113], v[116:119], off sc0 sc1
	s_cbranch_execnz .LBB0_241

; __device__ __forceinline__ unsigned cvt_pk_bf16(float lo, float hi) { const f32x2 v = {lo, hi}; return __builtin_bit_cast(unsigned, __builtin_convertvector(v, bf16x2_t)); }
; __device__ __forceinline__ float fast_silu(float g) { return g * __builtin_amdgcn_rcpf(1.0f + __builtin_amdgcn_exp2f(-1.4426950408889634f * g)); }
; __device__ __forceinline__ float sum4(f32x4 v) { return (v.x + v.y) + (v.z + v.w); }
; __device__ __forceinline__ float quad_sum(float t, int lane) { t += shx(t, 16, lane); t += shx(t, 32, lane); return t; }
;     template <int A0, int A1> __device__ __forceinline__ void run(const f32x4 (&acc)[2][2][4][2], const Unit& u, int wr, int wc, int fr, int fq) const {
;     ...
;             for (int m = 0; m < 4; ++m) {
;                 const int row = row0 + ai * 128 + m * 16;
;                 const float t = quad_sum(sum4(*(const f32x4*)(ssqp + (size_t)row * 16 + 4 * fq)), fq * 16 + fr);
;                 const float rr = rsqrtf(t * (1.0f / 1024.0f) + EPS);
;                 u32x4 w;
; #pragma unroll
;                 for (int n = 0; n < 2; ++n) {
;                     const f32x4 gg = acc[ai][0][m][n] * rr + bg[n], uu = acc[ai][1][m][n] * rr + bu[n];
;                     const float h0 = fast_silu(gg.x) * uu.x, h1 = fast_silu(gg.y) * uu.y, h2 = fast_silu(gg.z) * uu.z, h3 = fast_silu(gg.w) * uu.w;
;                     w[2 * n] = cvt_pk_bf16(h0, h1); w[2 * n + 1] = cvt_pk_bf16(h2, h3);
;                 }
;                 bf16_t* hp = H + (size_t)row * DFF + u.pn * 128 + wc * 32 + fq * 8;
;                 if (cnt) asm volatile("global_store_dwordx4 %0, %1, off sc0 sc1" :: "v"(hp), "v"(w) : "memory");
;                 else *(u32x4*)hp = w;
.LBB0_241:
	v_or_b32_e32 v112, 32, v160
	v_ashrrev_i32_e32 v113, 31, v112
	v_mov_b64_e32 v[114:115], v[228:229]
	v_mov_b64_e32 v[116:117], v[230:231]
	v_mov_b32_e32 v118, v115
	v_mov_b32_e32 v119, v116
	v_mov_b32_e32 v115, v117
	v_add_f32_e32 v114, v118, v114
	v_add_f32_e32 v115, v119, v115
	s_nop 0
	v_add_f32_e32 v113, v114, v115
	ds_bpermute_b32 v114, v164, v113
	s_waitcnt lgkmcnt(0)
	v_add_f32_e32 v113, v113, v114
	ds_bpermute_b32 v114, v165, v113
	s_waitcnt lgkmcnt(0)
	v_add_f32_e32 v113, v113, v114
	v_fmamk_f32 v113, v113, 0x3a800000, v252
	v_cmp_gt_f32_e32 vcc, s49, v113
	v_mul_f32_e32 v114, 0x4b800000, v113
	s_nop 0
	v_cndmask_b32_e32 v113, v113, v114, vcc
	v_rsq_f32_e32 v113, v113
	s_nop 0
	v_mul_f32_e32 v114, 0x45800000, v113
	v_cndmask_b32_e32 v114, v113, v114, vcc
	v_fma_f32 v108, v108, v114, v44
	v_fma_f32 v109, v109, v114, v45
	v_fma_f32 v110, v110, v114, v46
	v_fma_f32 v111, v111, v114, v47
	v_mul_f32_e32 v113, 0xbfb8aa3b, v108
	v_exp_f32_e32 v113, v113
	v_fma_f32 v100, v100, v114, v40
	v_fma_f32 v101, v101, v114, v41
	v_fma_f32 v102, v102, v114, v42
	v_fma_f32 v103, v103, v114, v43
	v_fma_f32 v104, v104, v114, v36
	v_fma_f32 v105, v105, v114, v37
	v_add_f32_e32 v113, 1.0, v113
	v_rcp_f32_e32 v116, v113
	v_mul_f32_e32 v113, 0xbfb8aa3b, v109
	v_exp_f32_e32 v113, v113
	v_fma_f32 v96, v96, v114, v32
	v_fma_f32 v97, v97, v114, v33
	v_fma_f32 v98, v98, v114, v34
	v_fma_f32 v99, v99, v114, v35
	s_and_b64 vcc, exec, s[6:7]
	v_add_f32_e32 v113, 1.0, v113
	v_rcp_f32_e32 v117, v113
	s_nop 0
	v_mul_f32_e32 v108, v108, v116
	v_mul_f32_e32 v109, v109, v117
	s_nop 0
	v_mul_f32_e32 v100, v100, v108
	v_mul_f32_e32 v101, v101, v109
	v_mul_f32_e32 v108, 0xbfb8aa3b, v110
	v_mul_f32_e32 v109, 0xbfb8aa3b, v111
	v_exp_f32_e32 v108, v108
	v_exp_f32_e32 v109, v109
	v_cvt_pk_bf16_f32 v100, v100, v101
	v_add_f32_e32 v108, 1.0, v108
	v_add_f32_e32 v109, 1.0, v109
	v_rcp_f32_e32 v108, v108
	v_rcp_f32_e32 v109, v109
	s_nop 0
	v_mul_f32_e32 v108, v110, v108
	v_mul_f32_e32 v109, v111, v109
	s_nop 0
	v_mul_f32_e32 v102, v102, v108
	v_mul_f32_e32 v103, v103, v109
	s_nop 0
	v_cvt_pk_bf16_f32 v101, v102, v103
	v_fma_f32 v102, v106, v114, v38
	v_fma_f32 v103, v107, v114, v39
	v_mul_f32_e32 v106, 0xbfb8aa3b, v104
	v_mul_f32_e32 v107, 0xbfb8aa3b, v105
	v_exp_f32_e32 v106, v106
	v_exp_f32_e32 v107, v107
	v_add_f32_e32 v106, 1.0, v106
	v_add_f32_e32 v107, 1.0, v107
	v_rcp_f32_e32 v106, v106
	v_rcp_f32_e32 v107, v107
	s_nop 0
	v_mul_f32_e32 v104, v104, v106
	v_mul_f32_e32 v105, v105, v107
	s_nop 0
	v_mul_f32_e32 v96, v96, v104
	v_mul_f32_e32 v97, v97, v105
	v_mul_f32_e32 v104, 0xbfb8aa3b, v102
	v_mul_f32_e32 v105, 0xbfb8aa3b, v103
	v_exp_f32_e32 v104, v104
	v_exp_f32_e32 v105, v105
	v_add_f32_e32 v104, 1.0, v104
	v_add_f32_e32 v105, 1.0, v105
	v_rcp_f32_e32 v104, v104
	v_rcp_f32_e32 v105, v105
	s_nop 0
	v_mul_f32_e32 v102, v102, v104
	v_mul_f32_e32 v103, v103, v105
	s_nop 0
	v_mul_f32_e32 v98, v98, v102
	v_mul_f32_e32 v99, v99, v103
	v_cvt_pk_bf16_f32 v102, v96, v97
	v_mov_b64_e32 v[96:97], s[12:13]
	v_mad_i64_i32 v[96:97], s[20:21], v112, s1, v[96:97]
	v_lshl_add_u64 v[96:97], s[84:85], 1, v[96:97]
	v_lshl_add_u64 v[96:97], v[96:97], 0, s[52:53]
	v_cvt_pk_bf16_f32 v103, v98, v99
	v_lshl_add_u64 v[96:97], v[96:97], 0, v[128:129]
	s_cbranch_vccnz .LBB0_269
	global_store_dwordx4 v[96:97], v[100:103], off sc0 sc1
	s_cbranch_execnz .LBB0_244

; __device__ __forceinline__ unsigned cvt_pk_bf16(float lo, float hi) { const f32x2 v = {lo, hi}; return __builtin_bit_cast(unsigned, __builtin_convertvector(v, bf16x2_t)); }
; __device__ __forceinline__ float fast_silu(float g) { return g * __builtin_amdgcn_rcpf(1.0f + __builtin_amdgcn_exp2f(-1.4426950408889634f * g)); }
; __device__ __forceinline__ float sum4(f32x4 v) { return (v.x + v.y) + (v.z + v.w); }
; __device__ __forceinline__ float quad_sum(float t, int lane) { t += shx(t, 16, lane); t += shx(t, 32, lane); return t; }
;     template <int A0, int A1> __device__ __forceinline__ void run(const f32x4 (&acc)[2][2][4][2], const Unit& u, int wr, int wc, int fr, int fq) const {
;     ...
;             for (int m = 0; m < 4; ++m) {
;                 const int row = row0 + ai * 128 + m * 16;
;                 const float t = quad_sum(sum4(*(const f32x4*)(ssqp + (size_t)row * 16 + 4 * fq)), fq * 16 + fr);
;                 const float rr = rsqrtf(t * (1.0f / 1024.0f) + EPS);
;                 u32x4 w;
; #pragma unroll
;                 for (int n = 0; n < 2; ++n) {
;                     const f32x4 gg = acc[ai][0][m][n] * rr + bg[n], uu = acc[ai][1][m][n] * rr + bu[n];
;                     const float h0 = fast_silu(gg.x) * uu.x, h1 = fast_silu(gg.y) * uu.y, h2 = fast_silu(gg.z) * uu.z, h3 = fast_silu(gg.w) * uu.w;
;                     w[2 * n] = cvt_pk_bf16(h0, h1); w[2 * n + 1] = cvt_pk_bf16(h2, h3);
;                 }
;                 bf16_t* hp = H + (size_t)row * DFF + u.pn * 128 + wc * 32 + fq * 8;
;                 if (cnt) asm volatile("global_store_dwordx4 %0, %1, off sc0 sc1" :: "v"(hp), "v"(w) : "memory");
;                 else *(u32x4*)hp = w;
.LBB0_244:
	v_or_b32_e32 v96, 48, v160
	v_ashrrev_i32_e32 v97, 31, v96
	v_mov_b64_e32 v[98:99], v[232:233]
	v_mov_b64_e32 v[100:101], v[234:235]
	v_mov_b32_e32 v102, v99
	v_mov_b32_e32 v103, v100
	v_mov_b32_e32 v99, v101
	v_add_f32_e32 v98, v102, v98
	v_add_f32_e32 v99, v103, v99
	s_nop 0
	v_add_f32_e32 v97, v98, v99
	ds_bpermute_b32 v98, v164, v97
	s_waitcnt lgkmcnt(0)
	v_add_f32_e32 v97, v97, v98
	ds_bpermute_b32 v98, v165, v97
	s_waitcnt lgkmcnt(0)
	v_add_f32_e32 v97, v97, v98
	v_fmamk_f32 v97, v97, 0x3a800000, v252
	v_cmp_gt_f32_e32 vcc, s49, v97
	v_mul_f32_e32 v98, 0x4b800000, v97
	s_nop 0
	v_cndmask_b32_e32 v97, v97, v98, vcc
	v_rsq_f32_e32 v97, v97
	s_nop 0
	v_mul_f32_e32 v98, 0x45800000, v97
	v_cndmask_b32_e32 v98, v97, v98, vcc
	v_fma_f32 v92, v92, v98, v44
	v_fma_f32 v93, v93, v98, v45
	v_fma_f32 v94, v94, v98, v46
	v_fma_f32 v95, v95, v98, v47
	v_mul_f32_e32 v97, 0xbfb8aa3b, v92
	v_exp_f32_e32 v97, v97
	v_fma_f32 v84, v84, v98, v40
	v_fma_f32 v85, v85, v98, v41
	v_fma_f32 v86, v86, v98, v42
	v_fma_f32 v87, v87, v98, v43
	v_fma_f32 v88, v88, v98, v36
	v_fma_f32 v89, v89, v98, v37
	v_add_f32_e32 v97, 1.0, v97
	v_rcp_f32_e32 v100, v97
	v_mul_f32_e32 v97, 0xbfb8aa3b, v93
	v_exp_f32_e32 v97, v97
	v_fma_f32 v80, v80, v98, v32
	v_fma_f32 v81, v81, v98, v33
	v_fma_f32 v82, v82, v98, v34
	v_fma_f32 v83, v83, v98, v35
	s_and_b64 vcc, exec, s[6:7]
	v_add_f32_e32 v97, 1.0, v97
	v_rcp_f32_e32 v101, v97
	s_nop 0
	v_mul_f32_e32 v92, v92, v100
	v_mul_f32_e32 v93, v93, v101
	s_nop 0
	v_mul_f32_e32 v84, v84, v92
	v_mul_f32_e32 v85, v85, v93
	v_mul_f32_e32 v92, 0xbfb8aa3b, v94
	v_mul_f32_e32 v93, 0xbfb8aa3b, v95
	v_exp_f32_e32 v92, v92
	v_exp_f32_e32 v93, v93
	v_cvt_pk_bf16_f32 v84, v84, v85
	v_add_f32_e32 v92, 1.0, v92
	v_add_f32_e32 v93, 1.0, v93
	v_rcp_f32_e32 v92, v92
	v_rcp_f32_e32 v93, v93
	s_nop 0
	v_mul_f32_e32 v92, v94, v92
	v_mul_f32_e32 v93, v95, v93
	s_nop 0
	v_mul_f32_e32 v86, v86, v92
	v_mul_f32_e32 v87, v87, v93
	s_nop 0
	v_cvt_pk_bf16_f32 v85, v86, v87
	v_fma_f32 v86, v90, v98, v38
	v_fma_f32 v87, v91, v98, v39
	v_mul_f32_e32 v90, 0xbfb8aa3b, v88
	v_mul_f32_e32 v91, 0xbfb8aa3b, v89
	v_exp_f32_e32 v90, v90
	v_exp_f32_e32 v91, v91
	v_add_f32_e32 v90, 1.0, v90
	v_add_f32_e32 v91, 1.0, v91
	v_rcp_f32_e32 v90, v90
	v_rcp_f32_e32 v91, v91
	s_nop 0
	v_mul_f32_e32 v88, v88, v90
	v_mul_f32_e32 v89, v89, v91
	s_nop 0
	v_mul_f32_e32 v80, v80, v88
	v_mul_f32_e32 v81, v81, v89
	v_mul_f32_e32 v88, 0xbfb8aa3b, v86
	v_mul_f32_e32 v89, 0xbfb8aa3b, v87
	v_exp_f32_e32 v88, v88
	v_exp_f32_e32 v89, v89
	v_add_f32_e32 v88, 1.0, v88
	v_add_f32_e32 v89, 1.0, v89
	v_rcp_f32_e32 v88, v88
	v_rcp_f32_e32 v89, v89
	s_nop 0
	v_mul_f32_e32 v86, v86, v88
	v_mul_f32_e32 v87, v87, v89
	s_nop 0
	v_mul_f32_e32 v82, v82, v86
	v_mul_f32_e32 v83, v83, v87
	v_cvt_pk_bf16_f32 v86, v80, v81
	v_mov_b64_e32 v[80:81], s[12:13]
	v_mad_i64_i32 v[80:81], s[20:21], v96, s1, v[80:81]
	v_lshl_add_u64 v[80:81], s[84:85], 1, v[80:81]
	v_lshl_add_u64 v[80:81], v[80:81], 0, s[52:53]
	v_cvt_pk_bf16_f32 v87, v82, v83
	v_lshl_add_u64 v[80:81], v[80:81], 0, v[128:129]
	s_cbranch_vccnz .LBB0_270
	global_store_dwordx4 v[80:81], v[84:87], off sc0 sc1
	s_cbranch_execnz .LBB0_247

; __device__ __forceinline__ unsigned cvt_pk_bf16(float lo, float hi) { const f32x2 v = {lo, hi}; return __builtin_bit_cast(unsigned, __builtin_convertvector(v, bf16x2_t)); }
; __device__ __forceinline__ float fast_silu(float g) { return g * __builtin_amdgcn_rcpf(1.0f + __builtin_amdgcn_exp2f(-1.4426950408889634f * g)); }
; __device__ __forceinline__ float sum4(f32x4 v) { return (v.x + v.y) + (v.z + v.w); }
; __device__ __forceinline__ float quad_sum(float t, int lane) { t += shx(t, 16, lane); t += shx(t, 32, lane); return t; }
;     template <int A0, int A1> __device__ __forceinline__ void run(const f32x4 (&acc)[2][2][4][2], const Unit& u, int wr, int wc, int fr, int fq) const {
;     ...
;             for (int m = 0; m < 4; ++m) {
;                 const int row = row0 + ai * 128 + m * 16;
;                 const float t = quad_sum(sum4(*(const f32x4*)(ssqp + (size_t)row * 16 + 4 * fq)), fq * 16 + fr);
;                 const float rr = rsqrtf(t * (1.0f / 1024.0f) + EPS);
;                 u32x4 w;
; #pragma unroll
;                 for (int n = 0; n < 2; ++n) {
;                     const f32x4 gg = acc[ai][0][m][n] * rr + bg[n], uu = acc[ai][1][m][n] * rr + bu[n];
;                     const float h0 = fast_silu(gg.x) * uu.x, h1 = fast_silu(gg.y) * uu.y, h2 = fast_silu(gg.z) * uu.z, h3 = fast_silu(gg.w) * uu.w;
;                     w[2 * n] = cvt_pk_bf16(h0, h1); w[2 * n + 1] = cvt_pk_bf16(h2, h3);
;                 }
;                 bf16_t* hp = H + (size_t)row * DFF + u.pn * 128 + wc * 32 + fq * 8;
;                 if (cnt) asm volatile("global_store_dwordx4 %0, %1, off sc0 sc1" :: "v"(hp), "v"(w) : "memory");
;                 else *(u32x4*)hp = w;
.LBB0_247:
	v_add_u32_e32 v80, 0x80, v160
	v_ashrrev_i32_e32 v81, 31, v80
	v_mov_b64_e32 v[82:83], v[240:241]
	v_mov_b64_e32 v[84:85], v[242:243]
	v_mov_b32_e32 v86, v83
	v_mov_b32_e32 v87, v84
	v_mov_b32_e32 v83, v85
	v_add_f32_e32 v82, v86, v82
	v_add_f32_e32 v83, v87, v83
	s_nop 0
	v_add_f32_e32 v81, v82, v83
	ds_bpermute_b32 v82, v164, v81
	s_waitcnt lgkmcnt(0)
	v_add_f32_e32 v81, v81, v82
	ds_bpermute_b32 v82, v165, v81
	s_waitcnt lgkmcnt(0)
	v_add_f32_e32 v81, v81, v82
	v_fmamk_f32 v81, v81, 0x3a800000, v252
	v_cmp_gt_f32_e32 vcc, s49, v81
	v_mul_f32_e32 v82, 0x4b800000, v81
	s_nop 0
	v_cndmask_b32_e32 v81, v81, v82, vcc
	v_rsq_f32_e32 v81, v81
	s_nop 0
	v_mul_f32_e32 v82, 0x45800000, v81
	v_cndmask_b32_e32 v82, v81, v82, vcc
	v_fma_f32 v76, v76, v82, v44
	v_fma_f32 v77, v77, v82, v45
	v_fma_f32 v78, v78, v82, v46
	v_fma_f32 v79, v79, v82, v47
	v_mul_f32_e32 v81, 0xbfb8aa3b, v76
	v_exp_f32_e32 v81, v81
	v_fma_f32 v68, v68, v82, v40
	v_fma_f32 v69, v69, v82, v41
	v_fma_f32 v70, v70, v82, v42
	v_fma_f32 v71, v71, v82, v43
	v_fma_f32 v72, v72, v82, v36
	v_fma_f32 v73, v73, v82, v37
	v_add_f32_e32 v81, 1.0, v81
	v_rcp_f32_e32 v84, v81
	v_mul_f32_e32 v81, 0xbfb8aa3b, v77
	v_exp_f32_e32 v81, v81
	v_fma_f32 v64, v64, v82, v32
	v_fma_f32 v65, v65, v82, v33
	v_fma_f32 v66, v66, v82, v34
	v_fma_f32 v67, v67, v82, v35
	s_and_b64 vcc, exec, s[6:7]
	v_add_f32_e32 v81, 1.0, v81
	v_rcp_f32_e32 v85, v81
	s_nop 0
	v_mul_f32_e32 v76, v76, v84
	v_mul_f32_e32 v77, v77, v85
	s_nop 0
	v_mul_f32_e32 v68, v68, v76
	v_mul_f32_e32 v69, v69, v77
	v_mul_f32_e32 v76, 0xbfb8aa3b, v78
	v_mul_f32_e32 v77, 0xbfb8aa3b, v79
	v_exp_f32_e32 v76, v76
	v_exp_f32_e32 v77, v77
	v_cvt_pk_bf16_f32 v68, v68, v69
	v_add_f32_e32 v76, 1.0, v76
	v_add_f32_e32 v77, 1.0, v77
	v_rcp_f32_e32 v76, v76
	v_rcp_f32_e32 v77, v77
	s_nop 0
	v_mul_f32_e32 v76, v78, v76
	v_mul_f32_e32 v77, v79, v77
	s_nop 0
	v_mul_f32_e32 v70, v70, v76
	v_mul_f32_e32 v71, v71, v77
	s_nop 0
	v_cvt_pk_bf16_f32 v69, v70, v71
	v_fma_f32 v70, v74, v82, v38
	v_fma_f32 v71, v75, v82, v39
	v_mul_f32_e32 v74, 0xbfb8aa3b, v72
	v_mul_f32_e32 v75, 0xbfb8aa3b, v73
	v_exp_f32_e32 v74, v74
	v_exp_f32_e32 v75, v75
	v_add_f32_e32 v74, 1.0, v74
	v_add_f32_e32 v75, 1.0, v75
	v_rcp_f32_e32 v74, v74
	v_rcp_f32_e32 v75, v75
	s_nop 0
	v_mul_f32_e32 v72, v72, v74
	v_mul_f32_e32 v73, v73, v75
	s_nop 0
	v_mul_f32_e32 v64, v64, v72
	v_mul_f32_e32 v65, v65, v73
	v_mul_f32_e32 v72, 0xbfb8aa3b, v70
	v_mul_f32_e32 v73, 0xbfb8aa3b, v71
	v_exp_f32_e32 v72, v72
	v_exp_f32_e32 v73, v73
	v_add_f32_e32 v72, 1.0, v72
	v_add_f32_e32 v73, 1.0, v73
	v_rcp_f32_e32 v72, v72
	v_rcp_f32_e32 v73, v73
	s_nop 0
	v_mul_f32_e32 v70, v70, v72
	v_mul_f32_e32 v71, v71, v73
	s_nop 0
	v_mul_f32_e32 v66, v66, v70
	v_mul_f32_e32 v67, v67, v71
	v_cvt_pk_bf16_f32 v70, v64, v65
	v_mov_b64_e32 v[64:65], s[12:13]
	v_mad_i64_i32 v[64:65], s[20:21], v80, s1, v[64:65]
	v_lshl_add_u64 v[64:65], s[84:85], 1, v[64:65]
	v_lshl_add_u64 v[64:65], v[64:65], 0, s[52:53]
	v_cvt_pk_bf16_f32 v71, v66, v67
	v_lshl_add_u64 v[64:65], v[64:65], 0, v[128:129]
	s_cbranch_vccnz .LBB0_271
	global_store_dwordx4 v[64:65], v[68:71], off sc0 sc1
	s_cbranch_execnz .LBB0_250

; __device__ __forceinline__ unsigned cvt_pk_bf16(float lo, float hi) { const f32x2 v = {lo, hi}; return __builtin_bit_cast(unsigned, __builtin_convertvector(v, bf16x2_t)); }
; __device__ __forceinline__ float fast_silu(float g) { return g * __builtin_amdgcn_rcpf(1.0f + __builtin_amdgcn_exp2f(-1.4426950408889634f * g)); }
; __device__ __forceinline__ float sum4(f32x4 v) { return (v.x + v.y) + (v.z + v.w); }
; __device__ __forceinline__ float quad_sum(float t, int lane) { t += shx(t, 16, lane); t += shx(t, 32, lane); return t; }
;     template <int A0, int A1> __device__ __forceinline__ void run(const f32x4 (&acc)[2][2][4][2], const Unit& u, int wr, int wc, int fr, int fq) const {
;     ...
;             for (int m = 0; m < 4; ++m) {
;                 const int row = row0 + ai * 128 + m * 16;
;                 const float t = quad_sum(sum4(*(const f32x4*)(ssqp + (size_t)row * 16 + 4 * fq)), fq * 16 + fr);
;                 const float rr = rsqrtf(t * (1.0f / 1024.0f) + EPS);
;                 u32x4 w;
; #pragma unroll
;                 for (int n = 0; n < 2; ++n) {
;                     const f32x4 gg = acc[ai][0][m][n] * rr + bg[n], uu = acc[ai][1][m][n] * rr + bu[n];
;                     const float h0 = fast_silu(gg.x) * uu.x, h1 = fast_silu(gg.y) * uu.y, h2 = fast_silu(gg.z) * uu.z, h3 = fast_silu(gg.w) * uu.w;
;                     w[2 * n] = cvt_pk_bf16(h0, h1); w[2 * n + 1] = cvt_pk_bf16(h2, h3);
;                 }
;                 bf16_t* hp = H + (size_t)row * DFF + u.pn * 128 + wc * 32 + fq * 8;
;                 if (cnt) asm volatile("global_store_dwordx4 %0, %1, off sc0 sc1" :: "v"(hp), "v"(w) : "memory");
;                 else *(u32x4*)hp = w;
.LBB0_250:
	v_add_u32_e32 v64, 0x90, v160
	v_ashrrev_i32_e32 v65, 31, v64
	v_mov_b64_e32 v[66:67], v[244:245]
	v_mov_b64_e32 v[68:69], v[246:247]
	v_mov_b32_e32 v70, v67
	v_mov_b32_e32 v71, v68
	v_mov_b32_e32 v67, v69
	v_add_f32_e32 v66, v70, v66
	v_add_f32_e32 v67, v71, v67
	s_nop 0
	v_add_f32_e32 v65, v66, v67
	ds_bpermute_b32 v66, v164, v65
	s_waitcnt lgkmcnt(0)
	v_add_f32_e32 v65, v65, v66
	ds_bpermute_b32 v66, v165, v65
	s_waitcnt lgkmcnt(0)
	v_add_f32_e32 v65, v65, v66
	v_fmamk_f32 v65, v65, 0x3a800000, v252
	v_cmp_gt_f32_e32 vcc, s49, v65
	v_mul_f32_e32 v66, 0x4b800000, v65
	s_nop 0
	v_cndmask_b32_e32 v65, v65, v66, vcc
	v_rsq_f32_e32 v65, v65
	s_nop 0
	v_mul_f32_e32 v66, 0x45800000, v65
	v_cndmask_b32_e32 v66, v65, v66, vcc
	v_fma_f32 v60, v60, v66, v44
	v_fma_f32 v61, v61, v66, v45
	v_fma_f32 v62, v62, v66, v46
	v_fma_f32 v63, v63, v66, v47
	v_mul_f32_e32 v65, 0xbfb8aa3b, v60
	v_exp_f32_e32 v65, v65
	v_fma_f32 v52, v52, v66, v40
	v_fma_f32 v53, v53, v66, v41
	v_fma_f32 v54, v54, v66, v42
	v_fma_f32 v55, v55, v66, v43
	v_fma_f32 v56, v56, v66, v36
	v_fma_f32 v57, v57, v66, v37
	v_add_f32_e32 v65, 1.0, v65
	v_rcp_f32_e32 v68, v65
	v_mul_f32_e32 v65, 0xbfb8aa3b, v61
	v_exp_f32_e32 v65, v65
	v_fma_f32 v48, v48, v66, v32
	v_fma_f32 v49, v49, v66, v33
	v_fma_f32 v50, v50, v66, v34
	v_fma_f32 v51, v51, v66, v35
	s_and_b64 vcc, exec, s[6:7]
	v_add_f32_e32 v65, 1.0, v65
	v_rcp_f32_e32 v69, v65
	s_nop 0
	v_mul_f32_e32 v60, v60, v68
	v_mul_f32_e32 v61, v61, v69
	s_nop 0
	v_mul_f32_e32 v52, v52, v60
	v_mul_f32_e32 v53, v53, v61
	v_mul_f32_e32 v60, 0xbfb8aa3b, v62
	v_mul_f32_e32 v61, 0xbfb8aa3b, v63
	v_exp_f32_e32 v60, v60
	v_exp_f32_e32 v61, v61
	v_cvt_pk_bf16_f32 v52, v52, v53
	v_add_f32_e32 v60, 1.0, v60
	v_add_f32_e32 v61, 1.0, v61
	v_rcp_f32_e32 v60, v60
	v_rcp_f32_e32 v61, v61
	s_nop 0
	v_mul_f32_e32 v60, v62, v60
	v_mul_f32_e32 v61, v63, v61
	s_nop 0
	v_mul_f32_e32 v54, v54, v60
	v_mul_f32_e32 v55, v55, v61
	s_nop 0
	v_cvt_pk_bf16_f32 v53, v54, v55
	v_fma_f32 v54, v58, v66, v38
	v_fma_f32 v55, v59, v66, v39
	v_mul_f32_e32 v58, 0xbfb8aa3b, v56
	v_mul_f32_e32 v59, 0xbfb8aa3b, v57
	v_exp_f32_e32 v58, v58
	v_exp_f32_e32 v59, v59
	v_add_f32_e32 v58, 1.0, v58
	v_add_f32_e32 v59, 1.0, v59
	v_rcp_f32_e32 v58, v58
	v_rcp_f32_e32 v59, v59
	s_nop 0
	v_mul_f32_e32 v56, v56, v58
	v_mul_f32_e32 v57, v57, v59
	s_nop 0
	v_mul_f32_e32 v48, v48, v56
	v_mul_f32_e32 v49, v49, v57
	v_mul_f32_e32 v56, 0xbfb8aa3b, v54
	v_mul_f32_e32 v57, 0xbfb8aa3b, v55
	v_exp_f32_e32 v56, v56
	v_exp_f32_e32 v57, v57
	v_add_f32_e32 v56, 1.0, v56
	v_add_f32_e32 v57, 1.0, v57
	v_rcp_f32_e32 v56, v56
	v_rcp_f32_e32 v57, v57
	s_nop 0
	v_mul_f32_e32 v54, v54, v56
	v_mul_f32_e32 v55, v55, v57
	s_nop 0
	v_mul_f32_e32 v50, v50, v54
	v_mul_f32_e32 v51, v51, v55
	v_cvt_pk_bf16_f32 v54, v48, v49
	v_mov_b64_e32 v[48:49], s[12:13]
	v_mad_i64_i32 v[48:49], s[20:21], v64, s1, v[48:49]
	v_lshl_add_u64 v[48:49], s[84:85], 1, v[48:49]
	v_lshl_add_u64 v[48:49], v[48:49], 0, s[52:53]
	v_cvt_pk_bf16_f32 v55, v50, v51
	v_lshl_add_u64 v[48:49], v[48:49], 0, v[128:129]
	s_cbranch_vccnz .LBB0_272
	global_store_dwordx4 v[48:49], v[52:55], off sc0 sc1
	s_cbranch_execnz .LBB0_253

; __device__ __forceinline__ unsigned cvt_pk_bf16(float lo, float hi) { const f32x2 v = {lo, hi}; return __builtin_bit_cast(unsigned, __builtin_convertvector(v, bf16x2_t)); }
; __device__ __forceinline__ float fast_silu(float g) { return g * __builtin_amdgcn_rcpf(1.0f + __builtin_amdgcn_exp2f(-1.4426950408889634f * g)); }
; __device__ __forceinline__ float sum4(f32x4 v) { return (v.x + v.y) + (v.z + v.w); }
; __device__ __forceinline__ float quad_sum(float t, int lane) { t += shx(t, 16, lane); t += shx(t, 32, lane); return t; }
;     template <int A0, int A1> __device__ __forceinline__ void run(const f32x4 (&acc)[2][2][4][2], const Unit& u, int wr, int wc, int fr, int fq) const {
;     ...
;             for (int m = 0; m < 4; ++m) {
;                 const int row = row0 + ai * 128 + m * 16;
;                 const float t = quad_sum(sum4(*(const f32x4*)(ssqp + (size_t)row * 16 + 4 * fq)), fq * 16 + fr);
;                 const float rr = rsqrtf(t * (1.0f / 1024.0f) + EPS);
;                 u32x4 w;
; #pragma unroll
;                 for (int n = 0; n < 2; ++n) {
;                     const f32x4 gg = acc[ai][0][m][n] * rr + bg[n], uu = acc[ai][1][m][n] * rr + bu[n];
;                     const float h0 = fast_silu(gg.x) * uu.x, h1 = fast_silu(gg.y) * uu.y, h2 = fast_silu(gg.z) * uu.z, h3 = fast_silu(gg.w) * uu.w;
;                     w[2 * n] = cvt_pk_bf16(h0, h1); w[2 * n + 1] = cvt_pk_bf16(h2, h3);
;                 }
;                 bf16_t* hp = H + (size_t)row * DFF + u.pn * 128 + wc * 32 + fq * 8;
;                 if (cnt) asm volatile("global_store_dwordx4 %0, %1, off sc0 sc1" :: "v"(hp), "v"(w) : "memory");
;                 else *(u32x4*)hp = w;
.LBB0_253:
	v_add_u32_e32 v48, 0xa0, v160
	v_ashrrev_i32_e32 v49, 31, v48
	v_mov_b64_e32 v[50:51], v[248:249]
	v_mov_b64_e32 v[52:53], v[250:251]
	v_mov_b32_e32 v54, v51
	v_mov_b32_e32 v55, v52
	v_mov_b32_e32 v51, v53
	v_add_f32_e32 v50, v54, v50
	v_add_f32_e32 v51, v55, v51
	s_nop 0
	v_add_f32_e32 v49, v50, v51
	ds_bpermute_b32 v50, v164, v49
	s_waitcnt lgkmcnt(0)
	v_add_f32_e32 v49, v49, v50
	ds_bpermute_b32 v50, v165, v49
	s_waitcnt lgkmcnt(0)
	v_add_f32_e32 v49, v49, v50
	v_fmamk_f32 v49, v49, 0x3a800000, v252
	v_cmp_gt_f32_e32 vcc, s49, v49
	v_mul_f32_e32 v50, 0x4b800000, v49
	s_nop 0
	v_cndmask_b32_e32 v49, v49, v50, vcc
	v_rsq_f32_e32 v49, v49
	s_nop 0
	v_mul_f32_e32 v50, 0x45800000, v49
	v_cndmask_b32_e32 v50, v49, v50, vcc
	v_fma_f32 v28, v28, v50, v44
	v_fma_f32 v29, v29, v50, v45
	v_fma_f32 v30, v30, v50, v46
	v_fma_f32 v31, v31, v50, v47
	v_mul_f32_e32 v49, 0xbfb8aa3b, v28
	v_exp_f32_e32 v49, v49
	v_fma_f32 v20, v20, v50, v40
	v_fma_f32 v21, v21, v50, v41
	v_fma_f32 v22, v22, v50, v42
	v_fma_f32 v23, v23, v50, v43
	v_fma_f32 v24, v24, v50, v36
	v_fma_f32 v25, v25, v50, v37
	v_add_f32_e32 v49, 1.0, v49
	v_rcp_f32_e32 v52, v49
	v_mul_f32_e32 v49, 0xbfb8aa3b, v29
	v_exp_f32_e32 v49, v49
	v_fma_f32 v16, v16, v50, v32
	v_fma_f32 v17, v17, v50, v33
	v_fma_f32 v18, v18, v50, v34
	v_fma_f32 v19, v19, v50, v35
	s_and_b64 vcc, exec, s[6:7]
	v_add_f32_e32 v49, 1.0, v49
	v_rcp_f32_e32 v53, v49
	s_nop 0
	v_mul_f32_e32 v28, v28, v52
	v_mul_f32_e32 v29, v29, v53
	s_nop 0
	v_mul_f32_e32 v20, v20, v28
	v_mul_f32_e32 v21, v21, v29
	v_mul_f32_e32 v28, 0xbfb8aa3b, v30
	v_mul_f32_e32 v29, 0xbfb8aa3b, v31
	v_exp_f32_e32 v28, v28
	v_exp_f32_e32 v29, v29
	v_cvt_pk_bf16_f32 v20, v20, v21
	v_add_f32_e32 v28, 1.0, v28
	v_add_f32_e32 v29, 1.0, v29
	v_rcp_f32_e32 v28, v28
	v_rcp_f32_e32 v29, v29
	s_nop 0
	v_mul_f32_e32 v28, v30, v28
	v_mul_f32_e32 v29, v31, v29
	s_nop 0
	v_mul_f32_e32 v22, v22, v28
	v_mul_f32_e32 v23, v23, v29
	s_nop 0
	v_cvt_pk_bf16_f32 v21, v22, v23
	v_fma_f32 v22, v26, v50, v38
	v_fma_f32 v23, v27, v50, v39
	v_mul_f32_e32 v26, 0xbfb8aa3b, v24
	v_mul_f32_e32 v27, 0xbfb8aa3b, v25
	v_exp_f32_e32 v26, v26
	v_exp_f32_e32 v27, v27
	v_add_f32_e32 v26, 1.0, v26
	v_add_f32_e32 v27, 1.0, v27
	v_rcp_f32_e32 v26, v26
	v_rcp_f32_e32 v27, v27
	s_nop 0
	v_mul_f32_e32 v24, v24, v26
	v_mul_f32_e32 v25, v25, v27
	s_nop 0
	v_mul_f32_e32 v16, v16, v24
	v_mul_f32_e32 v17, v17, v25
	v_mul_f32_e32 v24, 0xbfb8aa3b, v22
	v_mul_f32_e32 v25, 0xbfb8aa3b, v23
	v_exp_f32_e32 v24, v24
	v_exp_f32_e32 v25, v25
	v_add_f32_e32 v24, 1.0, v24
	v_add_f32_e32 v25, 1.0, v25
	v_rcp_f32_e32 v24, v24
	v_rcp_f32_e32 v25, v25
	s_nop 0
	v_mul_f32_e32 v22, v22, v24
	v_mul_f32_e32 v23, v23, v25
	s_nop 0
	v_mul_f32_e32 v18, v18, v22
	v_mul_f32_e32 v19, v19, v23
	v_cvt_pk_bf16_f32 v22, v16, v17
	v_mov_b64_e32 v[16:17], s[12:13]
	v_mad_i64_i32 v[16:17], s[20:21], v48, s1, v[16:17]
	v_lshl_add_u64 v[16:17], s[84:85], 1, v[16:17]
	v_lshl_add_u64 v[16:17], v[16:17], 0, s[52:53]
	v_cvt_pk_bf16_f32 v23, v18, v19
	v_lshl_add_u64 v[16:17], v[16:17], 0, v[128:129]
	s_cbranch_vccnz .LBB0_273
	global_store_dwordx4 v[16:17], v[20:23], off sc0 sc1
	s_cbranch_execnz .LBB0_256

; __device__ __forceinline__ unsigned cvt_pk_bf16(float lo, float hi) { const f32x2 v = {lo, hi}; return __builtin_bit_cast(unsigned, __builtin_convertvector(v, bf16x2_t)); }
; __device__ __forceinline__ float fast_silu(float g) { return g * __builtin_amdgcn_rcpf(1.0f + __builtin_amdgcn_exp2f(-1.4426950408889634f * g)); }
; __device__ __forceinline__ float sum4(f32x4 v) { return (v.x + v.y) + (v.z + v.w); }
; __device__ __forceinline__ float quad_sum(float t, int lane) { t += shx(t, 16, lane); t += shx(t, 32, lane); return t; }
;     template <int A0, int A1> __device__ __forceinline__ void run(const f32x4 (&acc)[2][2][4][2], const Unit& u, int wr, int wc, int fr, int fq) const {
;     ...
;             for (int m = 0; m < 4; ++m) {
;                 const int row = row0 + ai * 128 + m * 16;
;                 const float t = quad_sum(sum4(*(const f32x4*)(ssqp + (size_t)row * 16 + 4 * fq)), fq * 16 + fr);
;                 const float rr = rsqrtf(t * (1.0f / 1024.0f) + EPS);
;                 u32x4 w;
; #pragma unroll
;                 for (int n = 0; n < 2; ++n) {
;                     const f32x4 gg = acc[ai][0][m][n] * rr + bg[n], uu = acc[ai][1][m][n] * rr + bu[n];
;                     const float h0 = fast_silu(gg.x) * uu.x, h1 = fast_silu(gg.y) * uu.y, h2 = fast_silu(gg.z) * uu.z, h3 = fast_silu(gg.w) * uu.w;
;                     w[2 * n] = cvt_pk_bf16(h0, h1); w[2 * n + 1] = cvt_pk_bf16(h2, h3);
;                 }
;                 bf16_t* hp = H + (size_t)row * DFF + u.pn * 128 + wc * 32 + fq * 8;
;                 if (cnt) asm volatile("global_store_dwordx4 %0, %1, off sc0 sc1" :: "v"(hp), "v"(w) : "memory");
;                 else *(u32x4*)hp = w;
;             }
.LBB0_256:
	v_add_u32_e32 v16, 0xb0, v160
	v_ashrrev_i32_e32 v17, 31, v16
	s_waitcnt vmcnt(6)
	v_mov_b64_e32 v[18:19], v[224:225]
	v_mov_b64_e32 v[20:21], v[226:227]
	v_mov_b32_e32 v22, v19
	v_mov_b32_e32 v23, v20
	v_mov_b32_e32 v19, v21
	v_add_f32_e32 v18, v22, v18
	v_add_f32_e32 v19, v23, v19
	s_nop 0
	v_add_f32_e32 v17, v18, v19
	ds_bpermute_b32 v18, v164, v17
	s_waitcnt lgkmcnt(0)
	v_add_f32_e32 v17, v17, v18
	ds_bpermute_b32 v18, v165, v17
	s_waitcnt lgkmcnt(0)
	v_add_f32_e32 v17, v17, v18
	v_fmamk_f32 v17, v17, 0x3a800000, v252
	v_cmp_gt_f32_e32 vcc, s49, v17
	v_mul_f32_e32 v18, 0x4b800000, v17
	s_nop 0
	v_cndmask_b32_e32 v17, v17, v18, vcc
	v_rsq_f32_e32 v17, v17
	s_nop 0
	v_mul_f32_e32 v18, 0x45800000, v17
	v_cndmask_b32_e32 v18, v17, v18, vcc
	v_fma_f32 v12, v12, v18, v44
	v_fma_f32 v13, v13, v18, v45
	v_fma_f32 v14, v14, v18, v46
	v_fma_f32 v15, v15, v18, v47
	v_mul_f32_e32 v17, 0xbfb8aa3b, v12
	v_exp_f32_e32 v17, v17
	v_fma_f32 v4, v4, v18, v40
	v_fma_f32 v5, v5, v18, v41
	v_fma_f32 v6, v6, v18, v42
	v_fma_f32 v7, v7, v18, v43
	v_fma_f32 v8, v8, v18, v36
	v_fma_f32 v9, v9, v18, v37
	v_add_f32_e32 v17, 1.0, v17
	v_rcp_f32_e32 v20, v17
	v_mul_f32_e32 v17, 0xbfb8aa3b, v13
	v_exp_f32_e32 v17, v17
	v_fma_f32 v0, v0, v18, v32
	v_fma_f32 v1, v1, v18, v33
	v_fma_f32 v2, v2, v18, v34
	v_fma_f32 v3, v3, v18, v35
	s_and_b64 vcc, exec, s[6:7]
	v_add_f32_e32 v17, 1.0, v17
	v_rcp_f32_e32 v21, v17
	s_nop 0
	v_mul_f32_e32 v12, v12, v20
	v_mul_f32_e32 v13, v13, v21
	s_nop 0
	v_mul_f32_e32 v4, v4, v12
	v_mul_f32_e32 v5, v5, v13
	v_mul_f32_e32 v12, 0xbfb8aa3b, v14
	v_mul_f32_e32 v13, 0xbfb8aa3b, v15
	v_exp_f32_e32 v12, v12
	v_exp_f32_e32 v13, v13
	v_cvt_pk_bf16_f32 v4, v4, v5
	v_add_f32_e32 v12, 1.0, v12
	v_add_f32_e32 v13, 1.0, v13
	v_rcp_f32_e32 v12, v12
	v_rcp_f32_e32 v13, v13
	s_nop 0
	v_mul_f32_e32 v12, v14, v12
	v_mul_f32_e32 v13, v15, v13
	s_nop 0
	v_mul_f32_e32 v6, v6, v12
	v_mul_f32_e32 v7, v7, v13
	s_nop 0
	v_cvt_pk_bf16_f32 v5, v6, v7
	v_fma_f32 v6, v10, v18, v38
	v_fma_f32 v7, v11, v18, v39
	v_mul_f32_e32 v10, 0xbfb8aa3b, v8
	v_mul_f32_e32 v11, 0xbfb8aa3b, v9
	v_exp_f32_e32 v10, v10
	v_exp_f32_e32 v11, v11
	v_add_f32_e32 v10, 1.0, v10
	v_add_f32_e32 v11, 1.0, v11
	v_rcp_f32_e32 v10, v10
	v_rcp_f32_e32 v11, v11
	s_nop 0
	v_mul_f32_e32 v8, v8, v10
	v_mul_f32_e32 v9, v9, v11
	s_nop 0
	v_mul_f32_e32 v0, v0, v8
	v_mul_f32_e32 v1, v1, v9
	v_mul_f32_e32 v8, 0xbfb8aa3b, v6
	v_mul_f32_e32 v9, 0xbfb8aa3b, v7
	v_exp_f32_e32 v8, v8
	v_exp_f32_e32 v9, v9
	v_add_f32_e32 v8, 1.0, v8
	v_add_f32_e32 v9, 1.0, v9
	v_rcp_f32_e32 v8, v8
	v_rcp_f32_e32 v9, v9
	s_nop 0
	v_mul_f32_e32 v6, v6, v8
	v_mul_f32_e32 v7, v7, v9
	s_nop 0
	v_mul_f32_e32 v2, v2, v6
	v_mul_f32_e32 v3, v3, v7
	v_cvt_pk_bf16_f32 v6, v0, v1
	v_mov_b64_e32 v[0:1], s[12:13]
	v_mad_i64_i32 v[0:1], s[20:21], v16, s1, v[0:1]
	v_lshl_add_u64 v[0:1], s[84:85], 1, v[0:1]
	v_lshl_add_u64 v[0:1], v[0:1], 0, s[52:53]
	v_cvt_pk_bf16_f32 v7, v2, v3
	v_lshl_add_u64 v[0:1], v[0:1], 0, v[128:129]
	s_cbranch_vccnz .LBB0_274
	global_store_dwordx4 v[0:1], v[4:7], off sc0 sc1
	s_cbranch_execnz .LBB0_259
